# SGU unit: 11 of the 16 weight-tile loads and the 4 bias loads hoisted to the top of the unit (issued with the LayerNorm input rows), MFMA-section waits recounted for the 13 loads that remain
# baseline (speedup 1.0000x reference)
.LBB0_684:
	v_add_u32_e32 v2, 0xffffff90, v0
	v_mad_i64_i32 v[184:185], s[0:1], v2, s9, v[168:169]
	v_add_u32_e32 v2, 0xffffffa0, v0
	v_mad_i64_i32 v[182:183], s[0:1], v2, s9, v[168:169]
	v_add_u32_e32 v2, 0xffffffb0, v0
	v_mad_i64_i32 v[180:181], s[0:1], v2, s9, v[168:169]
	v_subrev_u32_e32 v2, 64, v0
	v_mad_i64_i32 v[178:179], s[0:1], v2, s9, v[168:169]
	v_subrev_u32_e32 v2, 48, v0
	v_mad_i64_i32 v[176:177], s[0:1], v2, s9, v[168:169]
	v_subrev_u32_e32 v2, 32, v0
	v_mad_i64_i32 v[174:175], s[0:1], v2, s9, v[168:169]
	v_add_u32_e32 v2, -16, v0
	v_mad_i64_i32 v[172:173], s[0:1], v2, s9, v[168:169]
	global_load_dwordx4 v[34:37], v[184:185], off offset:2560
	global_load_dwordx4 v[38:41], v[182:183], off offset:2560
	global_load_dwordx4 v[30:33], v[180:181], off offset:2560
	global_load_dwordx4 v[26:29], v[178:179], off offset:2560
	global_load_dwordx4 v[22:25], v[176:177], off offset:2560
	global_load_dwordx4 v[18:21], v[174:175], off offset:2560
	v_mad_i64_i32 v[170:171], s[0:1], v0, s9, v[168:169]
	global_load_dwordx4 v[14:17], v[172:173], off offset:2560
	global_load_dwordx4 v[10:13], v[170:171], off offset:2560
	global_load_dwordx4 v[2:5], v[154:155], off offset:16
	global_load_dwordx4 v[6:9], v[154:155], off
	global_load_dwordx4 v[94:97], v[156:157], off
	global_load_dwordx4 v[90:93], v[156:157], off offset:64
	global_load_dwordx4 v[86:89], v[156:157], off offset:128
	global_load_dwordx4 v[82:85], v[156:157], off offset:192
	global_load_dword v212, v[158:159], off
	global_load_dwordx4 v[78:81], v[160:161], off
	global_load_dwordx4 v[74:77], v[160:161], off offset:64
	global_load_dwordx4 v[70:73], v[160:161], off offset:128
	global_load_dwordx4 v[66:69], v[160:161], off offset:192
	global_load_dword v211, v[162:163], off offset:64
	global_load_dwordx4 v[62:65], v[164:165], off
	global_load_dwordx4 v[58:61], v[164:165], off offset:64
	global_load_dwordx4 v[54:57], v[164:165], off offset:128
	global_load_dword v210, v[162:163], off offset:128
	global_load_dword v209, v[162:163], off offset:192
	s_waitcnt vmcnt(24)
	v_lshlrev_b32_e32 v50, 16, v34
	v_and_b32_e32 v51, 0xffff0000, v34
	v_add_f32_e32 v52, 0, v50
	v_lshlrev_b32_e32 v46, 16, v35
	v_add_f32_e32 v52, v52, v51
	v_add_f32_e32 v53, v52, v46
	v_mul_f32_e32 v52, v50, v50
	v_and_b32_e32 v47, 0xffff0000, v35
	v_mov_b32_e32 v34, v46
	v_mov_b32_e32 v35, v50
	v_fmac_f32_e32 v52, v51, v51
	v_lshlrev_b32_e32 v44, 16, v36
	v_pk_fma_f32 v[34:35], v[34:35], v[34:35], v[52:53] op_sel_hi:[1,1,0]
	v_add_f32_e32 v53, v53, v47
	v_mul_f32_e32 v52, v47, v47
	v_and_b32_e32 v45, 0xffff0000, v36
	v_mov_b32_e32 v48, v44
	v_mov_b32_e32 v49, v47
	v_pk_add_f32 v[34:35], v[52:53], v[34:35] op_sel_hi:[0,1]
	v_add_f32_e32 v52, v53, v44
	v_lshlrev_b32_e32 v42, 16, v37
	v_pk_fma_f32 v[34:35], v[48:49], v[48:49], v[34:35]
	v_add_f32_e32 v49, v52, v45
	v_mul_f32_e32 v48, v45, v45
	v_and_b32_e32 v43, 0xffff0000, v37
	v_mov_b32_e32 v36, v42
	v_mov_b32_e32 v37, v45
	v_pk_add_f32 v[34:35], v[48:49], v[34:35] op_sel_hi:[0,1]
	v_pk_fma_f32 v[34:35], v[36:37], v[36:37], v[34:35]
	v_add_f32_e32 v49, v49, v42
	v_mul_f32_e32 v48, v43, v43
	v_mov_b32_e32 v35, v43
	v_pk_add_f32 v[34:35], v[48:49], v[34:35]
	s_nop 1
	v_add_f32_dpp v34, v34, v34 quad_perm:[1,0,3,2] row_mask:0xf bank_mask:0xf
	v_add_f32_dpp v35, v35, v35 quad_perm:[1,0,3,2] row_mask:0xf bank_mask:0xf
	s_nop 0
	v_add_f32_dpp v34, v34, v34 quad_perm:[2,3,0,1] row_mask:0xf bank_mask:0xf
	v_add_f32_dpp v35, v35, v35 quad_perm:[2,3,0,1] row_mask:0xf bank_mask:0xf
	s_nop 0
	v_add_f32_dpp v34, v34, v34 row_half_mirror row_mask:0xf bank_mask:0xf
	v_add_f32_dpp v35, v35, v35 row_half_mirror row_mask:0xf bank_mask:0xf
	s_nop 0
	v_add_f32_dpp v34, v34, v34 row_mirror row_mask:0xf bank_mask:0xf
	v_add_f32_dpp v35, v35, v35 row_mirror row_mask:0xf bank_mask:0xf
	s_nop 0
	v_mov_b32_e32 v36, v34
	v_mov_b32_e32 v37, v35
	s_nop 1
	v_permlane16_swap_b32_e32 v34, v36
	v_permlane16_swap_b32_e32 v35, v37
	s_nop 0
	v_pk_add_f32 v[34:35], v[34:35], v[36:37]
	s_nop 0
	v_pk_mul_f32 v[48:49], v[34:35], s[6:7] op_sel_hi:[1,0]
	s_nop 0
	v_fma_f32 v34, -v49, v49, v48
	v_max_f32_e32 v34, 0, v34
	v_add_f32_e32 v34, 0x3727c5ac, v34
	v_rsq_f32_e32 v52, v34
	v_pk_add_f32 v[34:35], v[50:51], v[48:49] op_sel:[0,1] neg_lo:[0,1] neg_hi:[0,1]
	v_pk_add_f32 v[36:37], v[46:47], v[48:49] op_sel:[0,1] neg_lo:[0,1] neg_hi:[0,1]
	v_pk_add_f32 v[42:43], v[42:43], v[48:49] op_sel:[0,1] neg_lo:[0,1] neg_hi:[0,1]
	v_pk_mul_f32 v[34:35], v[34:35], v[52:53] op_sel_hi:[1,0]
	v_pk_mul_f32 v[36:37], v[36:37], v[52:53] op_sel_hi:[1,0]
	s_waitcnt vmcnt(15)
	v_pk_mul_f32 v[34:35], v[6:7], v[34:35]
	v_pk_mul_f32 v[36:37], v[8:9], v[36:37]
	v_cvt_pk_bf16_f32 v34, v34, v35
	v_cvt_pk_bf16_f32 v35, v36, v37
	v_pk_add_f32 v[36:37], v[44:45], v[48:49] op_sel:[0,1] neg_lo:[0,1] neg_hi:[0,1]
	v_pk_mul_f32 v[42:43], v[42:43], v[52:53] op_sel_hi:[1,0]
	v_pk_mul_f32 v[36:37], v[36:37], v[52:53] op_sel_hi:[1,0]
	v_pk_mul_f32 v[42:43], v[4:5], v[42:43]
	v_pk_mul_f32 v[36:37], v[2:3], v[36:37]
	v_lshlrev_b32_e32 v46, 16, v38
	v_cvt_pk_bf16_f32 v36, v36, v37
	v_cvt_pk_bf16_f32 v37, v42, v43
	v_and_b32_e32 v47, 0xffff0000, v38
	v_add_f32_e32 v48, 0, v46
	ds_write_b128 v205, v[34:37]
	v_lshlrev_b32_e32 v36, 16, v40
	v_and_b32_e32 v37, 0xffff0000, v40
	v_lshlrev_b32_e32 v40, 16, v39
	v_add_f32_e32 v48, v48, v47
	v_add_f32_e32 v49, v48, v40
	v_mul_f32_e32 v48, v46, v46
	v_lshlrev_b32_e32 v42, 16, v41
	v_and_b32_e32 v43, 0xffff0000, v41
	v_and_b32_e32 v41, 0xffff0000, v39
	v_mov_b32_e32 v38, v40
	v_mov_b32_e32 v39, v46
	v_fmac_f32_e32 v48, v47, v47
	v_pk_fma_f32 v[38:39], v[38:39], v[38:39], v[48:49] op_sel_hi:[1,1,0]
	v_add_f32_e32 v49, v49, v41
	v_mul_f32_e32 v48, v41, v41
	v_mov_b32_e32 v44, v36
	v_mov_b32_e32 v45, v41
	v_pk_add_f32 v[38:39], v[48:49], v[38:39] op_sel_hi:[0,1]
	v_add_f32_e32 v48, v49, v36
	v_pk_fma_f32 v[38:39], v[44:45], v[44:45], v[38:39]
	v_add_f32_e32 v45, v48, v37
	v_mul_f32_e32 v44, v37, v37
	v_mov_b32_e32 v34, v42
	v_mov_b32_e32 v35, v37
	v_pk_add_f32 v[38:39], v[44:45], v[38:39] op_sel_hi:[0,1]
	v_pk_fma_f32 v[34:35], v[34:35], v[34:35], v[38:39]
	v_add_f32_e32 v45, v45, v42
	v_mul_f32_e32 v44, v43, v43
	v_mov_b32_e32 v35, v43
	v_pk_add_f32 v[34:35], v[44:45], v[34:35]
	s_nop 1
	v_add_f32_dpp v34, v34, v34 quad_perm:[1,0,3,2] row_mask:0xf bank_mask:0xf
	v_add_f32_dpp v35, v35, v35 quad_perm:[1,0,3,2] row_mask:0xf bank_mask:0xf
	s_nop 0
	v_add_f32_dpp v34, v34, v34 quad_perm:[2,3,0,1] row_mask:0xf bank_mask:0xf
	v_add_f32_dpp v35, v35, v35 quad_perm:[2,3,0,1] row_mask:0xf bank_mask:0xf
	s_nop 0
	v_add_f32_dpp v34, v34, v34 row_half_mirror row_mask:0xf bank_mask:0xf
	v_add_f32_dpp v35, v35, v35 row_half_mirror row_mask:0xf bank_mask:0xf
	s_nop 0
	v_add_f32_dpp v34, v34, v34 row_mirror row_mask:0xf bank_mask:0xf
	v_add_f32_dpp v35, v35, v35 row_mirror row_mask:0xf bank_mask:0xf
	s_nop 0
	v_mov_b32_e32 v38, v34
	v_mov_b32_e32 v39, v35
	s_nop 1
	v_permlane16_swap_b32_e32 v34, v38
	v_permlane16_swap_b32_e32 v35, v39
	s_nop 0
	v_pk_add_f32 v[34:35], v[34:35], v[38:39]
	s_nop 0
	v_pk_mul_f32 v[38:39], v[34:35], s[6:7] op_sel_hi:[1,0]
	s_nop 0
	v_fma_f32 v34, -v39, v39, v38
	v_max_f32_e32 v34, 0, v34
	v_add_f32_e32 v34, 0x3727c5ac, v34
	v_rsq_f32_e32 v44, v34
	v_pk_add_f32 v[34:35], v[46:47], v[38:39] op_sel:[0,1] neg_lo:[0,1] neg_hi:[0,1]
	v_pk_add_f32 v[40:41], v[40:41], v[38:39] op_sel:[0,1] neg_lo:[0,1] neg_hi:[0,1]
	v_pk_add_f32 v[36:37], v[36:37], v[38:39] op_sel:[0,1] neg_lo:[0,1] neg_hi:[0,1]
	v_pk_add_f32 v[38:39], v[42:43], v[38:39] op_sel:[0,1] neg_lo:[0,1] neg_hi:[0,1]
	v_pk_mul_f32 v[36:37], v[36:37], v[44:45] op_sel_hi:[1,0]
	v_pk_mul_f32 v[38:39], v[38:39], v[44:45] op_sel_hi:[1,0]
	v_lshlrev_b32_e32 v42, 16, v30
	v_pk_mul_f32 v[34:35], v[34:35], v[44:45] op_sel_hi:[1,0]
	v_pk_mul_f32 v[40:41], v[40:41], v[44:45] op_sel_hi:[1,0]
	v_pk_mul_f32 v[36:37], v[2:3], v[36:37]
	v_pk_mul_f32 v[38:39], v[4:5], v[38:39]
	v_and_b32_e32 v43, 0xffff0000, v30
	v_add_f32_e32 v44, 0, v42
	v_cvt_pk_bf16_f32 v36, v36, v37
	v_cvt_pk_bf16_f32 v37, v38, v39
	v_lshlrev_b32_e32 v38, 16, v31
	v_add_f32_e32 v44, v44, v43
	v_pk_mul_f32 v[34:35], v[6:7], v[34:35]
	v_pk_mul_f32 v[40:41], v[8:9], v[40:41]
	v_add_f32_e32 v45, v44, v38
	v_mul_f32_e32 v44, v42, v42
	v_cvt_pk_bf16_f32 v34, v34, v35
	v_cvt_pk_bf16_f32 v35, v40, v41
	v_and_b32_e32 v39, 0xffff0000, v31
	v_mov_b32_e32 v30, v38
	v_mov_b32_e32 v31, v42
	v_fmac_f32_e32 v44, v43, v43
	ds_write_b128 v205, v[34:37] offset:8448
	v_lshlrev_b32_e32 v36, 16, v32
	v_pk_fma_f32 v[30:31], v[30:31], v[30:31], v[44:45] op_sel_hi:[1,1,0]
	v_add_f32_e32 v45, v45, v39
	v_mul_f32_e32 v44, v39, v39
	v_and_b32_e32 v37, 0xffff0000, v32
	v_mov_b32_e32 v40, v36
	v_mov_b32_e32 v41, v39
	v_pk_add_f32 v[30:31], v[44:45], v[30:31] op_sel_hi:[0,1]
	v_add_f32_e32 v44, v45, v36
	v_lshlrev_b32_e32 v34, 16, v33
	v_pk_fma_f32 v[30:31], v[40:41], v[40:41], v[30:31]
	v_add_f32_e32 v41, v44, v37
	v_mul_f32_e32 v40, v37, v37
	v_and_b32_e32 v35, 0xffff0000, v33
	v_mov_b32_e32 v32, v34
	v_mov_b32_e32 v33, v37
	v_pk_add_f32 v[30:31], v[40:41], v[30:31] op_sel_hi:[0,1]
	v_pk_fma_f32 v[30:31], v[32:33], v[32:33], v[30:31]
	v_add_f32_e32 v41, v41, v34
	v_mul_f32_e32 v40, v35, v35
	v_mov_b32_e32 v31, v35
	v_pk_add_f32 v[30:31], v[40:41], v[30:31]
	s_nop 1
	v_add_f32_dpp v30, v30, v30 quad_perm:[1,0,3,2] row_mask:0xf bank_mask:0xf
	v_add_f32_dpp v31, v31, v31 quad_perm:[1,0,3,2] row_mask:0xf bank_mask:0xf
	s_nop 0
	v_add_f32_dpp v30, v30, v30 quad_perm:[2,3,0,1] row_mask:0xf bank_mask:0xf
	v_add_f32_dpp v31, v31, v31 quad_perm:[2,3,0,1] row_mask:0xf bank_mask:0xf
	s_nop 0
	v_add_f32_dpp v30, v30, v30 row_half_mirror row_mask:0xf bank_mask:0xf
	v_add_f32_dpp v31, v31, v31 row_half_mirror row_mask:0xf bank_mask:0xf
	s_nop 0
	v_add_f32_dpp v30, v30, v30 row_mirror row_mask:0xf bank_mask:0xf
	v_add_f32_dpp v31, v31, v31 row_mirror row_mask:0xf bank_mask:0xf
	s_nop 0
	v_mov_b32_e32 v32, v30
	v_mov_b32_e32 v33, v31
	s_nop 1
	v_permlane16_swap_b32_e32 v30, v32
	v_permlane16_swap_b32_e32 v31, v33
	s_nop 0
	v_pk_add_f32 v[30:31], v[30:31], v[32:33]
	s_nop 0
	v_pk_mul_f32 v[40:41], v[30:31], s[6:7] op_sel_hi:[1,0]
	s_nop 0
	v_fma_f32 v30, -v41, v41, v40
	v_max_f32_e32 v30, 0, v30
	v_add_f32_e32 v30, 0x3727c5ac, v30
	v_rsq_f32_e32 v44, v30
	v_pk_add_f32 v[30:31], v[42:43], v[40:41] op_sel:[0,1] neg_lo:[0,1] neg_hi:[0,1]
	v_pk_add_f32 v[32:33], v[38:39], v[40:41] op_sel:[0,1] neg_lo:[0,1] neg_hi:[0,1]
	v_pk_add_f32 v[34:35], v[34:35], v[40:41] op_sel:[0,1] neg_lo:[0,1] neg_hi:[0,1]
	v_pk_mul_f32 v[30:31], v[30:31], v[44:45] op_sel_hi:[1,0]
	v_pk_mul_f32 v[32:33], v[32:33], v[44:45] op_sel_hi:[1,0]
	v_pk_mul_f32 v[30:31], v[6:7], v[30:31]
	v_pk_mul_f32 v[32:33], v[8:9], v[32:33]
	v_cvt_pk_bf16_f32 v30, v30, v31
	v_cvt_pk_bf16_f32 v31, v32, v33
	v_pk_add_f32 v[32:33], v[36:37], v[40:41] op_sel:[0,1] neg_lo:[0,1] neg_hi:[0,1]
	v_pk_mul_f32 v[34:35], v[34:35], v[44:45] op_sel_hi:[1,0]
	v_pk_mul_f32 v[32:33], v[32:33], v[44:45] op_sel_hi:[1,0]
	v_lshlrev_b32_e32 v38, 16, v26
	v_pk_mul_f32 v[32:33], v[2:3], v[32:33]
	v_pk_mul_f32 v[34:35], v[4:5], v[34:35]
	v_and_b32_e32 v39, 0xffff0000, v26
	v_add_f32_e32 v40, 0, v38
	v_cvt_pk_bf16_f32 v32, v32, v33
	v_cvt_pk_bf16_f32 v33, v34, v35
	v_lshlrev_b32_e32 v34, 16, v27
	v_add_f32_e32 v40, v40, v39
	v_add_f32_e32 v41, v40, v34
	v_mul_f32_e32 v40, v38, v38
	v_and_b32_e32 v35, 0xffff0000, v27
	v_mov_b32_e32 v26, v34
	v_mov_b32_e32 v27, v38
	v_fmac_f32_e32 v40, v39, v39
	ds_write_b128 v205, v[30:33] offset:16896
	v_lshlrev_b32_e32 v32, 16, v28
	v_pk_fma_f32 v[26:27], v[26:27], v[26:27], v[40:41] op_sel_hi:[1,1,0]
	v_add_f32_e32 v41, v41, v35
	v_mul_f32_e32 v40, v35, v35
	v_and_b32_e32 v33, 0xffff0000, v28
	v_mov_b32_e32 v36, v32
	v_mov_b32_e32 v37, v35
	v_pk_add_f32 v[26:27], v[40:41], v[26:27] op_sel_hi:[0,1]
	v_add_f32_e32 v40, v41, v32
	v_lshlrev_b32_e32 v30, 16, v29
	v_pk_fma_f32 v[26:27], v[36:37], v[36:37], v[26:27]
	v_add_f32_e32 v37, v40, v33
	v_mul_f32_e32 v36, v33, v33
	v_and_b32_e32 v31, 0xffff0000, v29
	v_mov_b32_e32 v28, v30
	v_mov_b32_e32 v29, v33
	v_pk_add_f32 v[26:27], v[36:37], v[26:27] op_sel_hi:[0,1]
	v_pk_fma_f32 v[26:27], v[28:29], v[28:29], v[26:27]
	v_add_f32_e32 v37, v37, v30
	v_mul_f32_e32 v36, v31, v31
	v_mov_b32_e32 v27, v31
	v_pk_add_f32 v[26:27], v[36:37], v[26:27]
	s_nop 1
	v_add_f32_dpp v26, v26, v26 quad_perm:[1,0,3,2] row_mask:0xf bank_mask:0xf
	v_add_f32_dpp v27, v27, v27 quad_perm:[1,0,3,2] row_mask:0xf bank_mask:0xf
	s_nop 0
	v_add_f32_dpp v26, v26, v26 quad_perm:[2,3,0,1] row_mask:0xf bank_mask:0xf
	v_add_f32_dpp v27, v27, v27 quad_perm:[2,3,0,1] row_mask:0xf bank_mask:0xf
	s_nop 0
	v_add_f32_dpp v26, v26, v26 row_half_mirror row_mask:0xf bank_mask:0xf
	v_add_f32_dpp v27, v27, v27 row_half_mirror row_mask:0xf bank_mask:0xf
	s_nop 0
	v_add_f32_dpp v26, v26, v26 row_mirror row_mask:0xf bank_mask:0xf
	v_add_f32_dpp v27, v27, v27 row_mirror row_mask:0xf bank_mask:0xf
	s_nop 0
	v_mov_b32_e32 v28, v26
	v_mov_b32_e32 v29, v27
	s_nop 1
	v_permlane16_swap_b32_e32 v26, v28
	v_permlane16_swap_b32_e32 v27, v29
	s_nop 0
	v_pk_add_f32 v[26:27], v[26:27], v[28:29]
	s_nop 0
	v_pk_mul_f32 v[36:37], v[26:27], s[6:7] op_sel_hi:[1,0]
	s_nop 0
	v_fma_f32 v26, -v37, v37, v36
	v_max_f32_e32 v26, 0, v26
	v_add_f32_e32 v26, 0x3727c5ac, v26
	v_rsq_f32_e32 v40, v26
	v_pk_add_f32 v[26:27], v[38:39], v[36:37] op_sel:[0,1] neg_lo:[0,1] neg_hi:[0,1]
	v_pk_add_f32 v[28:29], v[34:35], v[36:37] op_sel:[0,1] neg_lo:[0,1] neg_hi:[0,1]
	v_pk_add_f32 v[30:31], v[30:31], v[36:37] op_sel:[0,1] neg_lo:[0,1] neg_hi:[0,1]
	v_pk_mul_f32 v[26:27], v[26:27], v[40:41] op_sel_hi:[1,0]
	v_pk_mul_f32 v[28:29], v[28:29], v[40:41] op_sel_hi:[1,0]
	v_pk_mul_f32 v[26:27], v[6:7], v[26:27]
	v_pk_mul_f32 v[28:29], v[8:9], v[28:29]
	v_cvt_pk_bf16_f32 v26, v26, v27
	v_cvt_pk_bf16_f32 v27, v28, v29
	v_pk_add_f32 v[28:29], v[32:33], v[36:37] op_sel:[0,1] neg_lo:[0,1] neg_hi:[0,1]
	v_pk_mul_f32 v[30:31], v[30:31], v[40:41] op_sel_hi:[1,0]
	v_pk_mul_f32 v[28:29], v[28:29], v[40:41] op_sel_hi:[1,0]
	v_lshlrev_b32_e32 v34, 16, v22
	v_pk_mul_f32 v[28:29], v[2:3], v[28:29]
	v_pk_mul_f32 v[30:31], v[4:5], v[30:31]
	v_and_b32_e32 v35, 0xffff0000, v22
	v_add_f32_e32 v36, 0, v34
	v_cvt_pk_bf16_f32 v28, v28, v29
	v_cvt_pk_bf16_f32 v29, v30, v31
	v_lshlrev_b32_e32 v30, 16, v23
	v_add_f32_e32 v36, v36, v35
	v_add_f32_e32 v37, v36, v30
	v_mul_f32_e32 v36, v34, v34
	v_and_b32_e32 v31, 0xffff0000, v23
	v_mov_b32_e32 v22, v30
	v_mov_b32_e32 v23, v34
	v_fmac_f32_e32 v36, v35, v35
	ds_write_b128 v205, v[26:29] offset:25344
	v_lshlrev_b32_e32 v28, 16, v24
	v_pk_fma_f32 v[22:23], v[22:23], v[22:23], v[36:37] op_sel_hi:[1,1,0]
	v_add_f32_e32 v37, v37, v31
	v_mul_f32_e32 v36, v31, v31
	v_and_b32_e32 v29, 0xffff0000, v24
	v_mov_b32_e32 v32, v28
	v_mov_b32_e32 v33, v31
	v_pk_add_f32 v[22:23], v[36:37], v[22:23] op_sel_hi:[0,1]
	v_add_f32_e32 v36, v37, v28
	v_lshlrev_b32_e32 v26, 16, v25
	v_pk_fma_f32 v[22:23], v[32:33], v[32:33], v[22:23]
	v_add_f32_e32 v33, v36, v29
	v_mul_f32_e32 v32, v29, v29
	v_and_b32_e32 v27, 0xffff0000, v25
	v_mov_b32_e32 v24, v26
	v_mov_b32_e32 v25, v29
	v_pk_add_f32 v[22:23], v[32:33], v[22:23] op_sel_hi:[0,1]
	v_pk_fma_f32 v[22:23], v[24:25], v[24:25], v[22:23]
	v_add_f32_e32 v33, v33, v26
	v_mul_f32_e32 v32, v27, v27
	v_mov_b32_e32 v23, v27
	v_pk_add_f32 v[22:23], v[32:33], v[22:23]
	s_nop 1
	v_add_f32_dpp v22, v22, v22 quad_perm:[1,0,3,2] row_mask:0xf bank_mask:0xf
	v_add_f32_dpp v23, v23, v23 quad_perm:[1,0,3,2] row_mask:0xf bank_mask:0xf
	s_nop 0
	v_add_f32_dpp v22, v22, v22 quad_perm:[2,3,0,1] row_mask:0xf bank_mask:0xf
	v_add_f32_dpp v23, v23, v23 quad_perm:[2,3,0,1] row_mask:0xf bank_mask:0xf
	s_nop 0
	v_add_f32_dpp v22, v22, v22 row_half_mirror row_mask:0xf bank_mask:0xf
	v_add_f32_dpp v23, v23, v23 row_half_mirror row_mask:0xf bank_mask:0xf
	s_nop 0
	v_add_f32_dpp v22, v22, v22 row_mirror row_mask:0xf bank_mask:0xf
	v_add_f32_dpp v23, v23, v23 row_mirror row_mask:0xf bank_mask:0xf
	s_nop 0
	v_mov_b32_e32 v24, v22
	v_mov_b32_e32 v25, v23
	s_nop 1
	v_permlane16_swap_b32_e32 v22, v24
	v_permlane16_swap_b32_e32 v23, v25
	s_nop 0
	v_pk_add_f32 v[22:23], v[22:23], v[24:25]
	s_nop 0
	v_pk_mul_f32 v[32:33], v[22:23], s[6:7] op_sel_hi:[1,0]
	s_nop 0
	v_fma_f32 v22, -v33, v33, v32
	v_max_f32_e32 v22, 0, v22
	v_add_f32_e32 v22, 0x3727c5ac, v22
	v_rsq_f32_e32 v36, v22
	v_pk_add_f32 v[22:23], v[34:35], v[32:33] op_sel:[0,1] neg_lo:[0,1] neg_hi:[0,1]
	v_pk_add_f32 v[24:25], v[30:31], v[32:33] op_sel:[0,1] neg_lo:[0,1] neg_hi:[0,1]
	v_pk_add_f32 v[26:27], v[26:27], v[32:33] op_sel:[0,1] neg_lo:[0,1] neg_hi:[0,1]
	v_pk_mul_f32 v[22:23], v[22:23], v[36:37] op_sel_hi:[1,0]
	v_pk_mul_f32 v[24:25], v[24:25], v[36:37] op_sel_hi:[1,0]
	v_pk_mul_f32 v[22:23], v[6:7], v[22:23]
	v_pk_mul_f32 v[24:25], v[8:9], v[24:25]
	v_cvt_pk_bf16_f32 v22, v22, v23
	v_cvt_pk_bf16_f32 v23, v24, v25
	v_pk_add_f32 v[24:25], v[28:29], v[32:33] op_sel:[0,1] neg_lo:[0,1] neg_hi:[0,1]
	v_pk_mul_f32 v[26:27], v[26:27], v[36:37] op_sel_hi:[1,0]
	v_pk_mul_f32 v[24:25], v[24:25], v[36:37] op_sel_hi:[1,0]
	v_lshlrev_b32_e32 v30, 16, v18
	v_pk_mul_f32 v[24:25], v[2:3], v[24:25]
	v_pk_mul_f32 v[26:27], v[4:5], v[26:27]
	v_and_b32_e32 v31, 0xffff0000, v18
	v_add_f32_e32 v32, 0, v30
	v_cvt_pk_bf16_f32 v24, v24, v25
	v_cvt_pk_bf16_f32 v25, v26, v27
	v_lshlrev_b32_e32 v26, 16, v19
	v_add_f32_e32 v32, v32, v31
	v_add_f32_e32 v33, v32, v26
	v_mul_f32_e32 v32, v30, v30
	v_and_b32_e32 v27, 0xffff0000, v19
	v_mov_b32_e32 v18, v26
	v_mov_b32_e32 v19, v30
	v_fmac_f32_e32 v32, v31, v31
	ds_write_b128 v205, v[22:25] offset:33792
	v_lshlrev_b32_e32 v24, 16, v20
	v_pk_fma_f32 v[18:19], v[18:19], v[18:19], v[32:33] op_sel_hi:[1,1,0]
	v_add_f32_e32 v33, v33, v27
	v_mul_f32_e32 v32, v27, v27
	v_and_b32_e32 v25, 0xffff0000, v20
	v_mov_b32_e32 v28, v24
	v_mov_b32_e32 v29, v27
	v_pk_add_f32 v[18:19], v[32:33], v[18:19] op_sel_hi:[0,1]
	v_add_f32_e32 v32, v33, v24
	v_lshlrev_b32_e32 v22, 16, v21
	v_pk_fma_f32 v[18:19], v[28:29], v[28:29], v[18:19]
	v_add_f32_e32 v29, v32, v25
	v_mul_f32_e32 v28, v25, v25
	v_and_b32_e32 v23, 0xffff0000, v21
	v_mov_b32_e32 v20, v22
	v_mov_b32_e32 v21, v25
	v_pk_add_f32 v[18:19], v[28:29], v[18:19] op_sel_hi:[0,1]
	v_pk_fma_f32 v[18:19], v[20:21], v[20:21], v[18:19]
	v_add_f32_e32 v29, v29, v22
	v_mul_f32_e32 v28, v23, v23
	v_mov_b32_e32 v19, v23
	v_pk_add_f32 v[18:19], v[28:29], v[18:19]
	s_nop 1
	v_add_f32_dpp v18, v18, v18 quad_perm:[1,0,3,2] row_mask:0xf bank_mask:0xf
	v_add_f32_dpp v19, v19, v19 quad_perm:[1,0,3,2] row_mask:0xf bank_mask:0xf
	s_nop 0
	v_add_f32_dpp v18, v18, v18 quad_perm:[2,3,0,1] row_mask:0xf bank_mask:0xf
	v_add_f32_dpp v19, v19, v19 quad_perm:[2,3,0,1] row_mask:0xf bank_mask:0xf
	s_nop 0
	v_add_f32_dpp v18, v18, v18 row_half_mirror row_mask:0xf bank_mask:0xf
	v_add_f32_dpp v19, v19, v19 row_half_mirror row_mask:0xf bank_mask:0xf
	s_nop 0
	v_add_f32_dpp v18, v18, v18 row_mirror row_mask:0xf bank_mask:0xf
	v_add_f32_dpp v19, v19, v19 row_mirror row_mask:0xf bank_mask:0xf
	s_nop 0
	v_mov_b32_e32 v20, v18
	v_mov_b32_e32 v21, v19
	s_nop 1
	v_permlane16_swap_b32_e32 v18, v20
	v_permlane16_swap_b32_e32 v19, v21
	s_nop 0
	v_pk_add_f32 v[18:19], v[18:19], v[20:21]
	s_nop 0
	v_pk_mul_f32 v[28:29], v[18:19], s[6:7] op_sel_hi:[1,0]
	s_nop 0
	v_fma_f32 v18, -v29, v29, v28
	v_max_f32_e32 v18, 0, v18
	v_add_f32_e32 v18, 0x3727c5ac, v18
	v_rsq_f32_e32 v32, v18
	v_pk_add_f32 v[18:19], v[30:31], v[28:29] op_sel:[0,1] neg_lo:[0,1] neg_hi:[0,1]
	v_pk_add_f32 v[20:21], v[26:27], v[28:29] op_sel:[0,1] neg_lo:[0,1] neg_hi:[0,1]
	v_pk_add_f32 v[22:23], v[22:23], v[28:29] op_sel:[0,1] neg_lo:[0,1] neg_hi:[0,1]
	v_pk_mul_f32 v[18:19], v[18:19], v[32:33] op_sel_hi:[1,0]
	v_pk_mul_f32 v[20:21], v[20:21], v[32:33] op_sel_hi:[1,0]
	v_pk_mul_f32 v[18:19], v[6:7], v[18:19]
	v_pk_mul_f32 v[20:21], v[8:9], v[20:21]
	v_cvt_pk_bf16_f32 v18, v18, v19
	v_cvt_pk_bf16_f32 v19, v20, v21
	v_pk_add_f32 v[20:21], v[24:25], v[28:29] op_sel:[0,1] neg_lo:[0,1] neg_hi:[0,1]
	v_pk_mul_f32 v[22:23], v[22:23], v[32:33] op_sel_hi:[1,0]
	v_pk_mul_f32 v[20:21], v[20:21], v[32:33] op_sel_hi:[1,0]
	v_lshlrev_b32_e32 v26, 16, v14
	v_pk_mul_f32 v[20:21], v[2:3], v[20:21]
	v_pk_mul_f32 v[22:23], v[4:5], v[22:23]
	v_and_b32_e32 v27, 0xffff0000, v14
	v_add_f32_e32 v28, 0, v26
	v_cvt_pk_bf16_f32 v20, v20, v21
	v_cvt_pk_bf16_f32 v21, v22, v23
	v_lshlrev_b32_e32 v22, 16, v15
	v_add_f32_e32 v28, v28, v27
	v_add_f32_e32 v29, v28, v22
	v_mul_f32_e32 v28, v26, v26
	v_and_b32_e32 v23, 0xffff0000, v15
	v_mov_b32_e32 v14, v22
	v_mov_b32_e32 v15, v26
	v_fmac_f32_e32 v28, v27, v27
	ds_write_b128 v205, v[18:21] offset:42240
	v_lshlrev_b32_e32 v20, 16, v16
	v_pk_fma_f32 v[14:15], v[14:15], v[14:15], v[28:29] op_sel_hi:[1,1,0]
	v_add_f32_e32 v29, v29, v23
	v_mul_f32_e32 v28, v23, v23
	v_and_b32_e32 v21, 0xffff0000, v16
	v_mov_b32_e32 v24, v20
	v_mov_b32_e32 v25, v23
	v_pk_add_f32 v[14:15], v[28:29], v[14:15] op_sel_hi:[0,1]
	v_add_f32_e32 v28, v29, v20
	v_lshlrev_b32_e32 v18, 16, v17
	v_pk_fma_f32 v[14:15], v[24:25], v[24:25], v[14:15]
	v_add_f32_e32 v25, v28, v21
	v_mul_f32_e32 v24, v21, v21
	v_and_b32_e32 v19, 0xffff0000, v17
	v_mov_b32_e32 v16, v18
	v_mov_b32_e32 v17, v21
	v_pk_add_f32 v[14:15], v[24:25], v[14:15] op_sel_hi:[0,1]
	v_pk_fma_f32 v[14:15], v[16:17], v[16:17], v[14:15]
	v_add_f32_e32 v25, v25, v18
	v_mul_f32_e32 v24, v19, v19
	v_mov_b32_e32 v15, v19
	v_pk_add_f32 v[14:15], v[24:25], v[14:15]
	s_nop 1
	v_add_f32_dpp v14, v14, v14 quad_perm:[1,0,3,2] row_mask:0xf bank_mask:0xf
	v_add_f32_dpp v15, v15, v15 quad_perm:[1,0,3,2] row_mask:0xf bank_mask:0xf
	s_nop 0
	v_add_f32_dpp v14, v14, v14 quad_perm:[2,3,0,1] row_mask:0xf bank_mask:0xf
	v_add_f32_dpp v15, v15, v15 quad_perm:[2,3,0,1] row_mask:0xf bank_mask:0xf
	s_nop 0
	v_add_f32_dpp v14, v14, v14 row_half_mirror row_mask:0xf bank_mask:0xf
	v_add_f32_dpp v15, v15, v15 row_half_mirror row_mask:0xf bank_mask:0xf
	s_nop 0
	v_add_f32_dpp v14, v14, v14 row_mirror row_mask:0xf bank_mask:0xf
	v_add_f32_dpp v15, v15, v15 row_mirror row_mask:0xf bank_mask:0xf
	s_nop 0
	v_mov_b32_e32 v16, v14
	v_mov_b32_e32 v17, v15
	s_nop 1
	v_permlane16_swap_b32_e32 v14, v16
	v_permlane16_swap_b32_e32 v15, v17
	s_nop 0
	v_pk_add_f32 v[14:15], v[14:15], v[16:17]
	s_nop 0
	v_pk_mul_f32 v[24:25], v[14:15], s[6:7] op_sel_hi:[1,0]
	s_nop 0
	v_fma_f32 v14, -v25, v25, v24
	v_max_f32_e32 v14, 0, v14
	v_add_f32_e32 v14, 0x3727c5ac, v14
	v_rsq_f32_e32 v28, v14
	v_pk_add_f32 v[14:15], v[26:27], v[24:25] op_sel:[0,1] neg_lo:[0,1] neg_hi:[0,1]
	v_pk_add_f32 v[16:17], v[22:23], v[24:25] op_sel:[0,1] neg_lo:[0,1] neg_hi:[0,1]
	v_pk_add_f32 v[18:19], v[18:19], v[24:25] op_sel:[0,1] neg_lo:[0,1] neg_hi:[0,1]
	v_pk_mul_f32 v[14:15], v[14:15], v[28:29] op_sel_hi:[1,0]
	v_pk_mul_f32 v[16:17], v[16:17], v[28:29] op_sel_hi:[1,0]
	v_pk_mul_f32 v[14:15], v[6:7], v[14:15]
	v_pk_mul_f32 v[16:17], v[8:9], v[16:17]
	v_cvt_pk_bf16_f32 v14, v14, v15
	v_cvt_pk_bf16_f32 v15, v16, v17
	v_pk_add_f32 v[16:17], v[20:21], v[24:25] op_sel:[0,1] neg_lo:[0,1] neg_hi:[0,1]
	v_pk_mul_f32 v[18:19], v[18:19], v[28:29] op_sel_hi:[1,0]
	v_pk_mul_f32 v[16:17], v[16:17], v[28:29] op_sel_hi:[1,0]
	v_lshlrev_b32_e32 v22, 16, v10
	v_pk_mul_f32 v[16:17], v[2:3], v[16:17]
	v_pk_mul_f32 v[18:19], v[4:5], v[18:19]
	v_and_b32_e32 v23, 0xffff0000, v10
	v_add_f32_e32 v24, 0, v22
	v_cvt_pk_bf16_f32 v16, v16, v17
	v_cvt_pk_bf16_f32 v17, v18, v19
	v_lshlrev_b32_e32 v18, 16, v11
	v_add_f32_e32 v24, v24, v23
	v_add_f32_e32 v25, v24, v18
	v_mul_f32_e32 v24, v22, v22
	v_and_b32_e32 v19, 0xffff0000, v11
	v_mov_b32_e32 v10, v18
	v_mov_b32_e32 v11, v22
	v_fmac_f32_e32 v24, v23, v23
	ds_write_b128 v205, v[14:17] offset:50688
	v_lshlrev_b32_e32 v16, 16, v12
	v_pk_fma_f32 v[10:11], v[10:11], v[10:11], v[24:25] op_sel_hi:[1,1,0]
	v_add_f32_e32 v25, v25, v19
	v_mul_f32_e32 v24, v19, v19
	v_and_b32_e32 v17, 0xffff0000, v12
	v_mov_b32_e32 v20, v16
	v_mov_b32_e32 v21, v19
	v_pk_add_f32 v[10:11], v[24:25], v[10:11] op_sel_hi:[0,1]
	v_add_f32_e32 v24, v25, v16
	v_lshlrev_b32_e32 v14, 16, v13
	v_pk_fma_f32 v[10:11], v[20:21], v[20:21], v[10:11]
	v_add_f32_e32 v21, v24, v17
	v_mul_f32_e32 v20, v17, v17
	v_and_b32_e32 v15, 0xffff0000, v13
	v_mov_b32_e32 v12, v14
	v_mov_b32_e32 v13, v17
	v_pk_add_f32 v[10:11], v[20:21], v[10:11] op_sel_hi:[0,1]
	v_pk_fma_f32 v[10:11], v[12:13], v[12:13], v[10:11]
	v_add_f32_e32 v21, v21, v14
	v_mul_f32_e32 v20, v15, v15
	v_mov_b32_e32 v11, v15
	v_pk_add_f32 v[10:11], v[20:21], v[10:11]
	s_nop 1
	v_add_f32_dpp v10, v10, v10 quad_perm:[1,0,3,2] row_mask:0xf bank_mask:0xf
	v_add_f32_dpp v11, v11, v11 quad_perm:[1,0,3,2] row_mask:0xf bank_mask:0xf
	s_nop 0
	v_add_f32_dpp v10, v10, v10 quad_perm:[2,3,0,1] row_mask:0xf bank_mask:0xf
	v_add_f32_dpp v11, v11, v11 quad_perm:[2,3,0,1] row_mask:0xf bank_mask:0xf
	s_nop 0
	v_add_f32_dpp v10, v10, v10 row_half_mirror row_mask:0xf bank_mask:0xf
	v_add_f32_dpp v11, v11, v11 row_half_mirror row_mask:0xf bank_mask:0xf
	s_nop 0
	v_add_f32_dpp v10, v10, v10 row_mirror row_mask:0xf bank_mask:0xf
	v_add_f32_dpp v11, v11, v11 row_mirror row_mask:0xf bank_mask:0xf
	s_nop 0
	v_mov_b32_e32 v12, v10
	v_mov_b32_e32 v13, v11
	s_nop 1
	v_permlane16_swap_b32_e32 v10, v12
	v_permlane16_swap_b32_e32 v11, v13
	s_nop 0
	v_pk_add_f32 v[10:11], v[10:11], v[12:13]
	s_nop 0
	v_pk_mul_f32 v[10:11], v[10:11], s[6:7] op_sel_hi:[1,0]
	s_nop 0
	v_fma_f32 v12, -v11, v11, v10
	v_max_f32_e32 v12, 0, v12
	v_add_f32_e32 v12, 0x3727c5ac, v12
	v_rsq_f32_e32 v12, v12
	v_pk_add_f32 v[20:21], v[22:23], v[10:11] op_sel:[0,1] neg_lo:[0,1] neg_hi:[0,1]
	v_pk_add_f32 v[18:19], v[18:19], v[10:11] op_sel:[0,1] neg_lo:[0,1] neg_hi:[0,1]
	v_pk_mul_f32 v[20:21], v[20:21], v[12:13] op_sel_hi:[1,0]
	v_pk_mul_f32 v[18:19], v[18:19], v[12:13] op_sel_hi:[1,0]
	v_pk_mul_f32 v[6:7], v[6:7], v[20:21]
	v_pk_mul_f32 v[8:9], v[8:9], v[18:19]
	v_cvt_pk_bf16_f32 v6, v6, v7
	v_cvt_pk_bf16_f32 v7, v8, v9
	v_pk_add_f32 v[8:9], v[16:17], v[10:11] op_sel:[0,1] neg_lo:[0,1] neg_hi:[0,1]
	s_nop 0
	v_pk_mul_f32 v[8:9], v[8:9], v[12:13] op_sel_hi:[1,0]
	s_nop 0
	v_pk_mul_f32 v[2:3], v[2:3], v[8:9]
	s_nop 0
	v_cvt_pk_bf16_f32 v8, v2, v3
	v_pk_add_f32 v[2:3], v[14:15], v[10:11] op_sel:[0,1] neg_lo:[0,1] neg_hi:[0,1]
	s_nop 0
	v_pk_mul_f32 v[2:3], v[2:3], v[12:13] op_sel_hi:[1,0]
	s_nop 0
	v_pk_mul_f32 v[2:3], v[4:5], v[2:3]
	s_nop 0
	v_cvt_pk_bf16_f32 v9, v2, v3
	ds_write_b128 v205, v[6:9] offset:59136
	global_load_dwordx4 v[50:53], v[184:185], off offset:512
	global_load_dwordx4 v[38:41], v[182:183], off offset:512
	global_load_dwordx4 v[34:37], v[180:181], off offset:512
	global_load_dwordx4 v[22:25], v[178:179], off offset:512
	global_load_dwordx4 v[18:21], v[176:177], off offset:512
	global_load_dwordx4 v[10:13], v[174:175], off offset:512
	global_load_dwordx4 v[6:9], v[172:173], off offset:512
	global_load_dwordx4 v[2:5], v[170:171], off offset:512
	global_load_dwordx4 v[46:49], v[164:165], off offset:192
	global_load_dwordx4 v[42:45], v[166:167], off
	global_load_dwordx4 v[30:33], v[166:167], off offset:64
	global_load_dwordx4 v[26:29], v[166:167], off offset:128
	global_load_dwordx4 v[14:17], v[166:167], off offset:192
	s_waitcnt lgkmcnt(0)
	s_barrier
	ds_read_b64_tr_b16 v[98:99], v206
	ds_read_b64_tr_b16 v[100:101], v206 offset:2112
	ds_read_b64_tr_b16 v[112:113], v206 offset:2144
	ds_read_b64_tr_b16 v[110:111], v206 offset:32
	ds_read_b64_tr_b16 v[106:107], v206 offset:64
	ds_read_b64_tr_b16 v[102:103], v206 offset:96
	ds_read_b64_tr_b16 v[108:109], v206 offset:2176
	ds_read_b64_tr_b16 v[104:105], v206 offset:2208
	ds_read_b64_tr_b16 v[118:119], v206 offset:16896
	s_waitcnt vmcnt(13) lgkmcnt(7)
	v_mfma_f32_16x16x32_bf16 v[114:117], v[98:101], v[94:97], 0
	ds_read_b64_tr_b16 v[120:121], v206 offset:19008
	ds_read_b64_tr_b16 v[124:125], v206 offset:19040
	s_waitcnt lgkmcnt(7)
	v_mfma_f32_16x16x32_bf16 v[130:133], v[110:113], v[94:97], 0
	s_waitcnt lgkmcnt(4)
	v_mfma_f32_16x16x32_bf16 v[136:139], v[106:109], v[94:97], 0
	s_waitcnt lgkmcnt(3)
	v_mfma_f32_16x16x32_bf16 v[140:143], v[102:105], v[94:97], 0
	ds_read_b64_tr_b16 v[122:123], v206 offset:16928
	ds_read_b64_tr_b16 v[126:127], v206 offset:16960
	ds_read_b64_tr_b16 v[94:95], v206 offset:16992
	ds_read_b64_tr_b16 v[128:129], v206 offset:19072
	ds_read_b64_tr_b16 v[96:97], v206 offset:19104
	ds_read_b64_tr_b16 v[134:135], v206 offset:33792
	s_waitcnt vmcnt(13) lgkmcnt(7)
	v_mfma_f32_16x16x32_bf16 v[144:147], v[118:121], v[90:93], v[114:117]
	s_waitcnt lgkmcnt(5)
	v_mfma_f32_16x16x32_bf16 v[214:217], v[122:125], v[90:93], v[130:133]
	s_waitcnt lgkmcnt(2)
	v_mfma_f32_16x16x32_bf16 v[218:221], v[126:129], v[90:93], v[136:139]
	s_nop 2
	ds_read_b64_tr_b16 v[136:137], v206 offset:35904
	ds_read_b64_tr_b16 v[132:133], v206 offset:35936
	s_waitcnt lgkmcnt(3)
	v_mfma_f32_16x16x32_bf16 v[138:141], v[94:97], v[90:93], v[140:143]
	ds_read_b64_tr_b16 v[130:131], v206 offset:33824
	ds_read_b64_tr_b16 v[114:115], v206 offset:33856
	ds_read_b64_tr_b16 v[90:91], v206 offset:33888
	ds_read_b64_tr_b16 v[116:117], v206 offset:35968
	ds_read_b64_tr_b16 v[92:93], v206 offset:36000
	s_waitcnt vmcnt(13) lgkmcnt(6)
	v_mfma_f32_16x16x32_bf16 v[222:225], v[134:137], v[86:89], v[144:147]
	s_nop 2
	ds_read_b64_tr_b16 v[146:147], v206 offset:50688
	s_waitcnt lgkmcnt(5)
	v_mfma_f32_16x16x32_bf16 v[214:217], v[130:133], v[86:89], v[214:217]
	ds_read_b64_tr_b16 v[148:149], v206 offset:52800
	ds_read_b64_tr_b16 v[144:145], v206 offset:52832
	s_waitcnt lgkmcnt(4)
	v_mfma_f32_16x16x32_bf16 v[218:221], v[114:117], v[86:89], v[218:221]
	s_waitcnt lgkmcnt(3)
	v_mfma_f32_16x16x32_bf16 v[226:229], v[90:93], v[86:89], v[138:141]
	ds_read_b64_tr_b16 v[142:143], v206 offset:50720
	s_nop 1
	ds_read_b64_tr_b16 v[138:139], v206 offset:50752
	ds_read_b64_tr_b16 v[86:87], v206 offset:50784
	ds_read_b64_tr_b16 v[140:141], v206 offset:52864
	ds_read_b64_tr_b16 v[88:89], v206 offset:52896
	s_waitcnt vmcnt(13) lgkmcnt(6)
	v_mfma_f32_16x16x32_bf16 v[222:225], v[146:149], v[82:85], v[222:225]
	s_waitcnt lgkmcnt(4)
	v_mfma_f32_16x16x32_bf16 v[214:217], v[142:145], v[82:85], v[214:217]
	s_waitcnt lgkmcnt(1)
	v_mfma_f32_16x16x32_bf16 v[218:221], v[138:141], v[82:85], v[218:221]
	s_waitcnt vmcnt(13)
	s_nop 2
	v_add_f32_e32 v213, v212, v222
	v_add_f32_e32 v222, v212, v223
	v_cvt_pk_f16_f32 v230, v213, v222
	s_waitcnt lgkmcnt(0)
	v_mfma_f32_16x16x32_bf16 v[82:85], v[86:89], v[82:85], v[226:229]
	v_add_f32_e32 v213, v212, v224
	s_waitcnt vmcnt(13)
	v_mfma_f32_16x16x32_bf16 v[226:229], v[98:101], v[78:81], 0
	v_mfma_f32_16x16x32_bf16 v[240:243], v[110:113], v[78:81], 0
	s_nop 3
	v_add_f32_e32 v82, v212, v82
	v_add_f32_e32 v83, v212, v83
	v_mfma_f32_16x16x32_bf16 v[244:247], v[106:109], v[78:81], 0
	v_mfma_f32_16x16x32_bf16 v[78:81], v[102:105], v[78:81], 0
	s_waitcnt vmcnt(13)
	v_mfma_f32_16x16x32_bf16 v[226:229], v[118:121], v[74:77], v[226:229]
	v_mfma_f32_16x16x32_bf16 v[240:243], v[122:125], v[74:77], v[240:243]
	v_mfma_f32_16x16x32_bf16 v[244:247], v[126:129], v[74:77], v[244:247]
	v_mfma_f32_16x16x32_bf16 v[74:77], v[94:97], v[74:77], v[78:81]
	s_waitcnt vmcnt(13)
	v_mfma_f32_16x16x32_bf16 v[78:81], v[134:137], v[70:73], v[226:229]
	v_mfma_f32_16x16x32_bf16 v[226:229], v[130:133], v[70:73], v[240:243]
	v_mfma_f32_16x16x32_bf16 v[240:243], v[114:117], v[70:73], v[244:247]
	v_mfma_f32_16x16x32_bf16 v[70:73], v[90:93], v[70:73], v[74:77]
	s_waitcnt vmcnt(13)
	v_mfma_f32_16x16x32_bf16 v[74:77], v[146:149], v[66:69], v[78:81]
	v_mfma_f32_16x16x32_bf16 v[78:81], v[142:145], v[66:69], v[226:229]
	v_mfma_f32_16x16x32_bf16 v[226:229], v[138:141], v[66:69], v[240:243]
	s_waitcnt vmcnt(13)
	s_nop 4
	v_add_f32_e32 v74, v211, v74
	v_add_f32_e32 v75, v211, v75
	v_mfma_f32_16x16x32_bf16 v[66:69], v[86:89], v[66:69], v[70:73]
	v_cvt_pk_f16_f32 v240, v82, v83
	v_add_f32_e32 v82, v212, v84
	v_add_f32_e32 v83, v212, v85
	v_add_f32_e32 v70, v212, v225
	v_cvt_pk_f16_f32 v231, v213, v70
	v_add_f32_e32 v213, v212, v214
	v_add_f32_e32 v214, v212, v215
	v_cvt_pk_f16_f32 v214, v213, v214
	v_add_f32_e32 v213, v212, v216
	v_add_f32_e32 v215, v212, v217
	s_waitcnt vmcnt(13)
	v_mfma_f32_16x16x32_bf16 v[70:73], v[98:101], v[62:65], 0
	v_cvt_pk_f16_f32 v215, v213, v215
	ds_write2_b64 v207, v[230:231], v[214:215] offset1:4
	v_add_f32_e32 v213, v212, v218
	v_mfma_f32_16x16x32_bf16 v[222:225], v[110:113], v[62:65], 0
	v_add_f32_e32 v218, v212, v219
	v_cvt_pk_f16_f32 v230, v213, v218
	v_add_f32_e32 v213, v212, v220
	v_mfma_f32_16x16x32_bf16 v[214:217], v[106:109], v[62:65], 0
	v_add_f32_e32 v218, v212, v221
	v_cvt_pk_f16_f32 v231, v213, v218
	v_cvt_pk_f16_f32 v241, v82, v83
	v_mfma_f32_16x16x32_bf16 v[62:65], v[102:105], v[62:65], 0
	v_cvt_pk_f16_f32 v212, v74, v75
	v_add_f32_e32 v74, v211, v76
	v_add_f32_e32 v75, v211, v77
	s_waitcnt vmcnt(13)
	v_mfma_f32_16x16x32_bf16 v[70:73], v[118:121], v[58:61], v[70:73]
	v_cvt_pk_f16_f32 v213, v74, v75
	v_add_f32_e32 v74, v211, v78
	v_add_f32_e32 v75, v211, v79
	v_mfma_f32_16x16x32_bf16 v[218:221], v[122:125], v[58:61], v[222:225]
	v_cvt_pk_f16_f32 v78, v74, v75
	v_add_f32_e32 v79, v211, v80
	v_add_f32_e32 v80, v211, v81
	v_mfma_f32_16x16x32_bf16 v[82:85], v[126:129], v[58:61], v[214:217]
	v_cvt_pk_f16_f32 v79, v79, v80
	v_add_u32_e32 v80, 0x2000, v207
	ds_write2_b64 v80, v[212:213], v[78:79] offset0:32 offset1:36
	v_mfma_f32_16x16x32_bf16 v[58:61], v[94:97], v[58:61], v[62:65]
	v_add_f32_e32 v66, v211, v66
	v_add_f32_e32 v67, v211, v67
	v_cvt_pk_f16_f32 v66, v66, v67
	s_waitcnt vmcnt(13)
	v_mfma_f32_16x16x32_bf16 v[62:65], v[134:137], v[54:57], v[70:73]
	v_add_f32_e32 v67, v211, v68
	v_add_f32_e32 v68, v211, v69
	v_cvt_pk_f16_f32 v67, v67, v68
	v_mfma_f32_16x16x32_bf16 v[70:73], v[130:133], v[54:57], v[218:221]
	ds_write2_b64 v207, v[230:231], v[240:241] offset0:8 offset1:12
	v_mfma_f32_16x16x32_bf16 v[74:77], v[114:117], v[54:57], v[82:85]
	v_mfma_f32_16x16x32_bf16 v[54:57], v[90:93], v[54:57], v[58:61]
	s_nop 2
	v_add_f32_e32 v58, v211, v226
	v_add_f32_e32 v59, v211, v227
	v_cvt_pk_f16_f32 v78, v58, v59
	s_waitcnt vmcnt(4)
	v_mfma_f32_16x16x32_bf16 v[58:61], v[146:149], v[46:49], v[62:65]
	s_nop 2
	v_add_f32_e32 v62, v211, v228
	v_add_f32_e32 v63, v211, v229
	v_cvt_pk_f16_f32 v79, v62, v63
	v_mfma_f32_16x16x32_bf16 v[62:65], v[142:145], v[46:49], v[70:73]
	ds_write2_b64 v80, v[78:79], v[66:67] offset0:40 offset1:44
	s_waitcnt vmcnt(4)
	v_add_f32_e32 v58, v210, v58
	v_add_f32_e32 v59, v210, v59
	v_mfma_f32_16x16x32_bf16 v[70:73], v[138:141], v[46:49], v[74:77]
	v_add_f32_e32 v66, v210, v60
	v_add_f32_e32 v67, v210, v61
	s_nop 0
	v_add_f32_e32 v62, v210, v62
	v_mfma_f32_16x16x32_bf16 v[46:49], v[86:89], v[46:49], v[54:57]
	v_add_f32_e32 v63, v210, v63
	v_cvt_pk_f16_f32 v74, v58, v59
	v_cvt_pk_f16_f32 v75, v66, v67
	s_waitcnt vmcnt(3)
	v_mfma_f32_16x16x32_bf16 v[54:57], v[98:101], v[42:45], 0
	v_cvt_pk_f16_f32 v62, v62, v63
	v_add_f32_e32 v63, v210, v64
	v_add_f32_e32 v64, v210, v65
	s_waitcnt vmcnt(2)
	v_mfma_f32_16x16x32_bf16 v[54:57], v[118:121], v[30:33], v[54:57]
	v_cvt_pk_f16_f32 v63, v63, v64
	v_add_u32_e32 v76, 0x4000, v207
	ds_write2_b64 v76, v[74:75], v[62:63] offset0:64 offset1:68
	v_mfma_f32_16x16x32_bf16 v[58:61], v[110:113], v[42:45], 0
	v_add_f32_e32 v62, v210, v70
	v_add_f32_e32 v63, v210, v71
	v_cvt_pk_f16_f32 v70, v62, v63
	v_mfma_f32_16x16x32_bf16 v[66:69], v[106:109], v[42:45], 0
	v_add_f32_e32 v62, v210, v72
	v_add_f32_e32 v63, v210, v73
	v_cvt_pk_f16_f32 v71, v62, v63
	v_mfma_f32_16x16x32_bf16 v[42:45], v[102:105], v[42:45], 0
	v_add_f32_e32 v46, v210, v46
	v_add_f32_e32 v47, v210, v47
	s_waitcnt vmcnt(1)
	v_mfma_f32_16x16x32_bf16 v[54:57], v[134:137], v[26:29], v[54:57]
	v_mfma_f32_16x16x32_bf16 v[58:61], v[122:125], v[30:33], v[58:61]
	v_mfma_f32_16x16x32_bf16 v[62:65], v[126:129], v[30:33], v[66:69]
	v_mfma_f32_16x16x32_bf16 v[30:33], v[94:97], v[30:33], v[42:45]
	s_nop 1
	v_cvt_pk_f16_f32 v66, v46, v47
	v_add_f32_e32 v46, v210, v48
	v_add_f32_e32 v47, v210, v49
	v_cvt_pk_f16_f32 v67, v46, v47
	s_waitcnt vmcnt(0)
	v_mfma_f32_16x16x32_bf16 v[46:49], v[146:149], v[14:17], v[54:57]
	ds_write2_b64 v76, v[70:71], v[66:67] offset0:72 offset1:76
	v_mfma_f32_16x16x32_bf16 v[54:57], v[130:133], v[26:29], v[58:61]
	v_mfma_f32_16x16x32_bf16 v[42:45], v[114:117], v[26:29], v[62:65]
	s_waitcnt vmcnt(0)
	s_nop 3
	v_add_f32_e32 v46, v209, v46
	v_add_f32_e32 v47, v209, v47
	v_cvt_pk_f16_f32 v58, v46, v47
	v_mfma_f32_16x16x32_bf16 v[26:29], v[90:93], v[26:29], v[30:33]
	v_add_f32_e32 v59, v209, v48
	v_add_f32_e32 v60, v209, v49
	v_cvt_pk_f16_f32 v59, v59, v60
	v_mfma_f32_16x16x32_bf16 v[46:49], v[142:145], v[14:17], v[54:57]
	v_mfma_f32_16x16x32_bf16 v[42:45], v[138:141], v[14:17], v[42:45]
	v_mfma_f32_16x16x32_bf16 v[14:17], v[86:89], v[14:17], v[26:29]
	s_nop 5
	v_add_f32_e32 v46, v209, v46
	v_add_f32_e32 v47, v209, v47
	v_cvt_pk_f16_f32 v46, v46, v47
	v_add_f32_e32 v47, v209, v48
	v_add_f32_e32 v48, v209, v49
	v_add_f32_e32 v14, v209, v14
	v_add_f32_e32 v15, v209, v15
	v_add_f32_e32 v42, v209, v42
	v_add_f32_e32 v43, v209, v43
	v_add_f32_e32 v30, v209, v44
	v_add_f32_e32 v31, v209, v45
	v_cvt_pk_f16_f32 v14, v14, v15
	v_add_f32_e32 v15, v209, v16
	v_add_f32_e32 v16, v209, v17
	v_cvt_pk_f16_f32 v47, v47, v48
	v_add_u32_e32 v48, 0x6000, v207
	v_cvt_pk_f16_f32 v42, v42, v43
	v_cvt_pk_f16_f32 v43, v30, v31
	v_cvt_pk_f16_f32 v15, v15, v16
	ds_write2_b64 v48, v[58:59], v[46:47] offset0:96 offset1:100
	ds_write2_b64 v48, v[42:43], v[14:15] offset0:104 offset1:108
	s_waitcnt lgkmcnt(0)
	s_barrier
	global_load_dwordx4 v[62:65], v[184:185], off offset:3072
	global_load_dwordx4 v[58:61], v[182:183], off offset:3072
	global_load_dwordx4 v[54:57], v[180:181], off offset:3072
	global_load_dwordx4 v[46:49], v[178:179], off offset:3072
	global_load_dwordx4 v[42:45], v[176:177], off offset:3072
	global_load_dwordx4 v[30:33], v[174:175], off offset:3072
	global_load_dwordx4 v[26:29], v[172:173], off offset:3072
	global_load_dwordx4 v[14:17], v[170:171], off offset:3072
	ds_read_b128 v[66:69], v208
	v_lshlrev_b32_e32 v70, 16, v50
	v_and_b32_e32 v71, 0xffff0000, v50
	s_waitcnt vmcnt(7)
	v_lshlrev_b32_e32 v72, 16, v62
	v_and_b32_e32 v73, 0xffff0000, v62
	s_waitcnt lgkmcnt(0)
	v_cvt_f32_f16_e32 v74, v66
	v_cvt_f32_f16_sdwa v75, v66 dst_sel:DWORD dst_unused:UNUSED_PAD src0_sel:WORD_1
	v_cvt_f32_f16_e32 v66, v67
	v_cvt_f32_f16_sdwa v67, v67 dst_sel:DWORD dst_unused:UNUSED_PAD src0_sel:WORD_1
	v_lshlrev_b32_e32 v62, 16, v63
	v_pk_mul_f32 v[70:71], v[70:71], v[74:75]
	v_and_b32_e32 v63, 0xffff0000, v63
	v_pk_mul_f32 v[70:71], v[70:71], v[72:73]
	s_add_i32 s16, s16, s5
	v_cvt_pk_bf16_f32 v50, v70, v71
	v_lshlrev_b32_e32 v70, 16, v51
	v_and_b32_e32 v71, 0xffff0000, v51
	v_pk_mul_f32 v[66:67], v[70:71], v[66:67]
	v_cvt_f32_f16_e32 v70, v68
	v_cvt_f32_f16_sdwa v71, v68 dst_sel:DWORD dst_unused:UNUSED_PAD src0_sel:WORD_1
	v_pk_mul_f32 v[62:63], v[66:67], v[62:63]
	v_lshlrev_b32_e32 v66, 16, v64
	v_cvt_pk_bf16_f32 v51, v62, v63
	v_lshlrev_b32_e32 v62, 16, v52
	v_and_b32_e32 v63, 0xffff0000, v52
	v_and_b32_e32 v67, 0xffff0000, v64
	v_pk_mul_f32 v[62:63], v[62:63], v[70:71]
	v_lshlrev_b32_e32 v64, 16, v65
	v_pk_mul_f32 v[62:63], v[62:63], v[66:67]
	v_cvt_f32_f16_e32 v66, v69
	v_cvt_f32_f16_sdwa v67, v69 dst_sel:DWORD dst_unused:UNUSED_PAD src0_sel:WORD_1
	v_cvt_pk_bf16_f32 v52, v62, v63
	v_lshlrev_b32_e32 v62, 16, v53
	v_and_b32_e32 v63, 0xffff0000, v53
	v_and_b32_e32 v65, 0xffff0000, v65
	v_pk_mul_f32 v[62:63], v[62:63], v[66:67]
	v_add_u32_e32 v0, s17, v0
	v_pk_mul_f32 v[62:63], v[62:63], v[64:65]
	s_waitcnt vmcnt(6)
	v_lshlrev_b32_e32 v64, 16, v58
	v_cvt_pk_bf16_f32 v53, v62, v63
	global_store_dwordx4 v[184:185], v[50:53], off offset:512
	ds_read_b128 v[50:53], v208 offset:8448
	v_lshlrev_b32_e32 v62, 16, v38
	v_and_b32_e32 v63, 0xffff0000, v38
	v_and_b32_e32 v65, 0xffff0000, v58
	v_lshlrev_b32_e32 v58, 16, v59
	s_waitcnt lgkmcnt(0)
	v_cvt_f32_f16_e32 v66, v50
	v_cvt_f32_f16_sdwa v67, v50 dst_sel:DWORD dst_unused:UNUSED_PAD src0_sel:WORD_1
	v_cvt_f32_f16_e32 v50, v51
	v_cvt_f32_f16_sdwa v51, v51 dst_sel:DWORD dst_unused:UNUSED_PAD src0_sel:WORD_1
	v_and_b32_e32 v59, 0xffff0000, v59
	v_pk_mul_f32 v[62:63], v[62:63], v[66:67]
	s_cmpk_lt_i32 s16, 0x180
	v_pk_mul_f32 v[62:63], v[62:63], v[64:65]
	s_nop 0
	v_cvt_pk_bf16_f32 v38, v62, v63
	v_lshlrev_b32_e32 v62, 16, v39
	v_and_b32_e32 v63, 0xffff0000, v39
	v_pk_mul_f32 v[50:51], v[62:63], v[50:51]
	v_cvt_f32_f16_e32 v62, v52
	v_cvt_f32_f16_sdwa v63, v52 dst_sel:DWORD dst_unused:UNUSED_PAD src0_sel:WORD_1
	v_pk_mul_f32 v[50:51], v[50:51], v[58:59]
	v_cvt_f32_f16_e32 v52, v53
	v_cvt_pk_bf16_f32 v39, v50, v51
	v_lshlrev_b32_e32 v50, 16, v40
	v_and_b32_e32 v51, 0xffff0000, v40
	v_cvt_f32_f16_sdwa v53, v53 dst_sel:DWORD dst_unused:UNUSED_PAD src0_sel:WORD_1
	v_lshlrev_b32_e32 v58, 16, v60
	v_and_b32_e32 v59, 0xffff0000, v60
	v_pk_mul_f32 v[50:51], v[50:51], v[62:63]
	s_nop 0
	v_pk_mul_f32 v[50:51], v[50:51], v[58:59]
	v_lshlrev_b32_e32 v58, 16, v61
	v_cvt_pk_bf16_f32 v40, v50, v51
	v_lshlrev_b32_e32 v50, 16, v41
	v_and_b32_e32 v51, 0xffff0000, v41
	v_and_b32_e32 v59, 0xffff0000, v61
	v_pk_mul_f32 v[50:51], v[50:51], v[52:53]
	s_waitcnt vmcnt(6)
	v_lshlrev_b32_e32 v52, 16, v54
	v_pk_mul_f32 v[50:51], v[50:51], v[58:59]
	v_and_b32_e32 v53, 0xffff0000, v54
	v_cvt_pk_bf16_f32 v41, v50, v51
	global_store_dwordx4 v[182:183], v[38:41], off offset:512
	ds_read_b128 v[38:41], v208 offset:16896
	v_lshlrev_b32_e32 v50, 16, v34
	v_and_b32_e32 v51, 0xffff0000, v34
	s_waitcnt lgkmcnt(0)
	v_cvt_f32_f16_e32 v58, v38
	v_cvt_f32_f16_sdwa v59, v38 dst_sel:DWORD dst_unused:UNUSED_PAD src0_sel:WORD_1
	v_cvt_f32_f16_e32 v38, v39
	v_cvt_f32_f16_sdwa v39, v39 dst_sel:DWORD dst_unused:UNUSED_PAD src0_sel:WORD_1
	v_pk_mul_f32 v[50:51], v[50:51], v[58:59]
	s_nop 0
	v_pk_mul_f32 v[50:51], v[50:51], v[52:53]
	v_lshlrev_b32_e32 v52, 16, v55
	v_cvt_pk_bf16_f32 v34, v50, v51
	v_lshlrev_b32_e32 v50, 16, v35
	v_and_b32_e32 v51, 0xffff0000, v35
	v_and_b32_e32 v53, 0xffff0000, v55
	v_pk_mul_f32 v[38:39], v[50:51], v[38:39]
	v_lshlrev_b32_e32 v50, 16, v56
	v_pk_mul_f32 v[38:39], v[38:39], v[52:53]
	v_cvt_f32_f16_e32 v52, v40
	v_cvt_f32_f16_sdwa v53, v40 dst_sel:DWORD dst_unused:UNUSED_PAD src0_sel:WORD_1
	v_cvt_pk_bf16_f32 v35, v38, v39
	v_lshlrev_b32_e32 v38, 16, v36
	v_and_b32_e32 v39, 0xffff0000, v36
	v_cvt_f32_f16_e32 v40, v41
	v_cvt_f32_f16_sdwa v41, v41 dst_sel:DWORD dst_unused:UNUSED_PAD src0_sel:WORD_1
	v_and_b32_e32 v51, 0xffff0000, v56
	v_pk_mul_f32 v[38:39], v[38:39], v[52:53]
	s_nop 0
	v_pk_mul_f32 v[38:39], v[38:39], v[50:51]
	v_lshlrev_b32_e32 v50, 16, v57
	v_cvt_pk_bf16_f32 v36, v38, v39
	v_lshlrev_b32_e32 v38, 16, v37
	v_and_b32_e32 v39, 0xffff0000, v37
	v_and_b32_e32 v51, 0xffff0000, v57
	v_pk_mul_f32 v[38:39], v[38:39], v[40:41]
	s_waitcnt vmcnt(6)
	v_lshlrev_b32_e32 v40, 16, v46
	v_pk_mul_f32 v[38:39], v[38:39], v[50:51]
	v_and_b32_e32 v41, 0xffff0000, v46
	v_cvt_pk_bf16_f32 v37, v38, v39
	global_store_dwordx4 v[180:181], v[34:37], off offset:512
	ds_read_b128 v[34:37], v208 offset:25344
	v_lshlrev_b32_e32 v38, 16, v22
	v_and_b32_e32 v39, 0xffff0000, v22
	s_waitcnt lgkmcnt(0)
	v_cvt_f32_f16_e32 v50, v34
	v_cvt_f32_f16_sdwa v51, v34 dst_sel:DWORD dst_unused:UNUSED_PAD src0_sel:WORD_1
	v_cvt_f32_f16_e32 v34, v35
	v_cvt_f32_f16_sdwa v35, v35 dst_sel:DWORD dst_unused:UNUSED_PAD src0_sel:WORD_1
	v_pk_mul_f32 v[38:39], v[38:39], v[50:51]
	s_nop 0
	v_pk_mul_f32 v[38:39], v[38:39], v[40:41]
	v_lshlrev_b32_e32 v40, 16, v47
	v_cvt_pk_bf16_f32 v22, v38, v39
	v_lshlrev_b32_e32 v38, 16, v23
	v_and_b32_e32 v39, 0xffff0000, v23
	v_and_b32_e32 v41, 0xffff0000, v47
	v_pk_mul_f32 v[34:35], v[38:39], v[34:35]
	v_lshlrev_b32_e32 v38, 16, v48
	v_pk_mul_f32 v[34:35], v[34:35], v[40:41]
	v_cvt_f32_f16_e32 v40, v36
	v_cvt_f32_f16_sdwa v41, v36 dst_sel:DWORD dst_unused:UNUSED_PAD src0_sel:WORD_1
	v_cvt_pk_bf16_f32 v23, v34, v35
	v_lshlrev_b32_e32 v34, 16, v24
	v_and_b32_e32 v35, 0xffff0000, v24
	v_cvt_f32_f16_e32 v36, v37
	v_cvt_f32_f16_sdwa v37, v37 dst_sel:DWORD dst_unused:UNUSED_PAD src0_sel:WORD_1
	v_and_b32_e32 v39, 0xffff0000, v48
	v_pk_mul_f32 v[34:35], v[34:35], v[40:41]
	s_nop 0
	v_pk_mul_f32 v[34:35], v[34:35], v[38:39]
	v_lshlrev_b32_e32 v38, 16, v49
	v_cvt_pk_bf16_f32 v24, v34, v35
	v_lshlrev_b32_e32 v34, 16, v25
	v_and_b32_e32 v35, 0xffff0000, v25
	v_and_b32_e32 v39, 0xffff0000, v49
	v_pk_mul_f32 v[34:35], v[34:35], v[36:37]
	s_waitcnt vmcnt(6)
	v_lshlrev_b32_e32 v36, 16, v42
	v_pk_mul_f32 v[34:35], v[34:35], v[38:39]
	v_and_b32_e32 v37, 0xffff0000, v42
	v_cvt_pk_bf16_f32 v25, v34, v35
	global_store_dwordx4 v[178:179], v[22:25], off offset:512
	ds_read_b128 v[22:25], v208 offset:33792
	v_lshlrev_b32_e32 v34, 16, v18
	v_and_b32_e32 v35, 0xffff0000, v18
	s_waitcnt lgkmcnt(0)
	v_cvt_f32_f16_e32 v38, v22
	v_cvt_f32_f16_sdwa v39, v22 dst_sel:DWORD dst_unused:UNUSED_PAD src0_sel:WORD_1
	v_cvt_f32_f16_e32 v22, v23
	v_cvt_f32_f16_sdwa v23, v23 dst_sel:DWORD dst_unused:UNUSED_PAD src0_sel:WORD_1
	v_pk_mul_f32 v[34:35], v[34:35], v[38:39]
	s_nop 0
	v_pk_mul_f32 v[34:35], v[34:35], v[36:37]
	v_lshlrev_b32_e32 v36, 16, v43
	v_cvt_pk_bf16_f32 v18, v34, v35
	v_lshlrev_b32_e32 v34, 16, v19
	v_and_b32_e32 v35, 0xffff0000, v19
	v_and_b32_e32 v37, 0xffff0000, v43
	v_pk_mul_f32 v[22:23], v[34:35], v[22:23]
	v_lshlrev_b32_e32 v34, 16, v44
	v_pk_mul_f32 v[22:23], v[22:23], v[36:37]
	v_cvt_f32_f16_e32 v36, v24
	v_cvt_f32_f16_sdwa v37, v24 dst_sel:DWORD dst_unused:UNUSED_PAD src0_sel:WORD_1
	v_cvt_pk_bf16_f32 v19, v22, v23
	v_lshlrev_b32_e32 v22, 16, v20
	v_and_b32_e32 v23, 0xffff0000, v20
	v_cvt_f32_f16_e32 v24, v25
	v_cvt_f32_f16_sdwa v25, v25 dst_sel:DWORD dst_unused:UNUSED_PAD src0_sel:WORD_1
	v_and_b32_e32 v35, 0xffff0000, v44
	v_pk_mul_f32 v[22:23], v[22:23], v[36:37]
	s_nop 0
	v_pk_mul_f32 v[22:23], v[22:23], v[34:35]
	v_lshlrev_b32_e32 v34, 16, v45
	v_cvt_pk_bf16_f32 v20, v22, v23
	v_lshlrev_b32_e32 v22, 16, v21
	v_and_b32_e32 v23, 0xffff0000, v21
	v_and_b32_e32 v35, 0xffff0000, v45
	v_pk_mul_f32 v[22:23], v[22:23], v[24:25]
	s_waitcnt vmcnt(6)
	v_lshlrev_b32_e32 v24, 16, v30
	v_pk_mul_f32 v[22:23], v[22:23], v[34:35]
	v_and_b32_e32 v25, 0xffff0000, v30
	v_cvt_pk_bf16_f32 v21, v22, v23
	global_store_dwordx4 v[176:177], v[18:21], off offset:512
	ds_read_b128 v[18:21], v208 offset:42240
	v_lshlrev_b32_e32 v22, 16, v10
	v_and_b32_e32 v23, 0xffff0000, v10
	s_waitcnt lgkmcnt(0)
	v_cvt_f32_f16_e32 v34, v18
	v_cvt_f32_f16_sdwa v35, v18 dst_sel:DWORD dst_unused:UNUSED_PAD src0_sel:WORD_1
	v_cvt_f32_f16_e32 v18, v19
	v_cvt_f32_f16_sdwa v19, v19 dst_sel:DWORD dst_unused:UNUSED_PAD src0_sel:WORD_1
	v_pk_mul_f32 v[22:23], v[22:23], v[34:35]
	s_nop 0
	v_pk_mul_f32 v[22:23], v[22:23], v[24:25]
	v_lshlrev_b32_e32 v24, 16, v31
	v_cvt_pk_bf16_f32 v10, v22, v23
	v_lshlrev_b32_e32 v22, 16, v11
	v_and_b32_e32 v23, 0xffff0000, v11
	v_and_b32_e32 v25, 0xffff0000, v31
	v_pk_mul_f32 v[18:19], v[22:23], v[18:19]
	v_lshlrev_b32_e32 v22, 16, v32
	v_pk_mul_f32 v[18:19], v[18:19], v[24:25]
	v_cvt_f32_f16_e32 v24, v20
	v_cvt_f32_f16_sdwa v25, v20 dst_sel:DWORD dst_unused:UNUSED_PAD src0_sel:WORD_1
	v_cvt_pk_bf16_f32 v11, v18, v19
	v_lshlrev_b32_e32 v18, 16, v12
	v_and_b32_e32 v19, 0xffff0000, v12
	v_cvt_f32_f16_e32 v20, v21
	v_cvt_f32_f16_sdwa v21, v21 dst_sel:DWORD dst_unused:UNUSED_PAD src0_sel:WORD_1
	v_and_b32_e32 v23, 0xffff0000, v32
	v_pk_mul_f32 v[18:19], v[18:19], v[24:25]
	s_nop 0
	v_pk_mul_f32 v[18:19], v[18:19], v[22:23]
	v_lshlrev_b32_e32 v22, 16, v33
	v_cvt_pk_bf16_f32 v12, v18, v19
	v_lshlrev_b32_e32 v18, 16, v13
	v_and_b32_e32 v19, 0xffff0000, v13
	v_and_b32_e32 v23, 0xffff0000, v33
	v_pk_mul_f32 v[18:19], v[18:19], v[20:21]
	s_waitcnt vmcnt(6)
	v_lshlrev_b32_e32 v20, 16, v26
	v_pk_mul_f32 v[18:19], v[18:19], v[22:23]
	v_and_b32_e32 v21, 0xffff0000, v26
	v_cvt_pk_bf16_f32 v13, v18, v19
	global_store_dwordx4 v[174:175], v[10:13], off offset:512
	ds_read_b128 v[10:13], v208 offset:50688
	v_lshlrev_b32_e32 v18, 16, v6
	v_and_b32_e32 v19, 0xffff0000, v6
	s_waitcnt lgkmcnt(0)
	v_cvt_f32_f16_e32 v22, v10
	v_cvt_f32_f16_sdwa v23, v10 dst_sel:DWORD dst_unused:UNUSED_PAD src0_sel:WORD_1
	v_cvt_f32_f16_e32 v10, v11
	v_cvt_f32_f16_sdwa v11, v11 dst_sel:DWORD dst_unused:UNUSED_PAD src0_sel:WORD_1
	v_pk_mul_f32 v[18:19], v[18:19], v[22:23]
	s_nop 0
	v_pk_mul_f32 v[18:19], v[18:19], v[20:21]
	v_lshlrev_b32_e32 v20, 16, v27
	v_cvt_pk_bf16_f32 v6, v18, v19
	v_lshlrev_b32_e32 v18, 16, v7
	v_and_b32_e32 v19, 0xffff0000, v7
	v_and_b32_e32 v21, 0xffff0000, v27
	v_pk_mul_f32 v[10:11], v[18:19], v[10:11]
	v_lshlrev_b32_e32 v18, 16, v28
	v_pk_mul_f32 v[10:11], v[10:11], v[20:21]
	v_cvt_f32_f16_e32 v20, v12
	v_cvt_f32_f16_sdwa v21, v12 dst_sel:DWORD dst_unused:UNUSED_PAD src0_sel:WORD_1
	v_cvt_pk_bf16_f32 v7, v10, v11
	v_lshlrev_b32_e32 v10, 16, v8
	v_and_b32_e32 v11, 0xffff0000, v8
	v_cvt_f32_f16_e32 v12, v13
	v_cvt_f32_f16_sdwa v13, v13 dst_sel:DWORD dst_unused:UNUSED_PAD src0_sel:WORD_1
	v_and_b32_e32 v19, 0xffff0000, v28
	v_pk_mul_f32 v[10:11], v[10:11], v[20:21]
	s_nop 0
	v_pk_mul_f32 v[10:11], v[10:11], v[18:19]
	v_lshlrev_b32_e32 v18, 16, v29
	v_cvt_pk_bf16_f32 v8, v10, v11
	v_lshlrev_b32_e32 v10, 16, v9
	v_and_b32_e32 v11, 0xffff0000, v9
	v_and_b32_e32 v19, 0xffff0000, v29
	v_pk_mul_f32 v[10:11], v[10:11], v[12:13]
	s_waitcnt vmcnt(6)
	v_lshlrev_b32_e32 v12, 16, v14
	v_pk_mul_f32 v[10:11], v[10:11], v[18:19]
	v_and_b32_e32 v13, 0xffff0000, v14
	v_cvt_pk_bf16_f32 v9, v10, v11
	global_store_dwordx4 v[172:173], v[6:9], off offset:512
	ds_read_b128 v[6:9], v208 offset:59136
	v_lshlrev_b32_e32 v10, 16, v2
	v_and_b32_e32 v11, 0xffff0000, v2
	s_waitcnt lgkmcnt(0)
	v_cvt_f32_f16_e32 v18, v6
	v_cvt_f32_f16_sdwa v19, v6 dst_sel:DWORD dst_unused:UNUSED_PAD src0_sel:WORD_1
	v_cvt_f32_f16_e32 v6, v7
	v_cvt_f32_f16_sdwa v7, v7 dst_sel:DWORD dst_unused:UNUSED_PAD src0_sel:WORD_1
	v_pk_mul_f32 v[10:11], v[10:11], v[18:19]
	s_nop 0
	v_pk_mul_f32 v[10:11], v[10:11], v[12:13]
	v_lshlrev_b32_e32 v12, 16, v15
	v_cvt_pk_bf16_f32 v2, v10, v11
	v_lshlrev_b32_e32 v10, 16, v3
	v_and_b32_e32 v11, 0xffff0000, v3
	v_and_b32_e32 v13, 0xffff0000, v15
	v_pk_mul_f32 v[6:7], v[10:11], v[6:7]
	v_lshlrev_b32_e32 v10, 16, v16
	v_pk_mul_f32 v[6:7], v[6:7], v[12:13]
	v_cvt_f32_f16_e32 v12, v8
	v_cvt_f32_f16_sdwa v13, v8 dst_sel:DWORD dst_unused:UNUSED_PAD src0_sel:WORD_1
	v_cvt_pk_bf16_f32 v3, v6, v7
	v_lshlrev_b32_e32 v6, 16, v4
	v_and_b32_e32 v7, 0xffff0000, v4
	v_cvt_f32_f16_e32 v8, v9
	v_cvt_f32_f16_sdwa v9, v9 dst_sel:DWORD dst_unused:UNUSED_PAD src0_sel:WORD_1
	v_and_b32_e32 v11, 0xffff0000, v16
	v_pk_mul_f32 v[6:7], v[6:7], v[12:13]
	s_nop 0
	v_pk_mul_f32 v[6:7], v[6:7], v[10:11]
	v_lshlrev_b32_e32 v10, 16, v17
	v_cvt_pk_bf16_f32 v4, v6, v7
	v_lshlrev_b32_e32 v6, 16, v5
	v_and_b32_e32 v7, 0xffff0000, v5
	v_and_b32_e32 v11, 0xffff0000, v17
	v_pk_mul_f32 v[6:7], v[6:7], v[8:9]
	s_nop 0
	v_pk_mul_f32 v[6:7], v[6:7], v[10:11]
	s_nop 0
	v_cvt_pk_bf16_f32 v5, v6, v7
	global_store_dwordx4 v[170:171], v[2:5], off offset:512
	s_barrier
	s_cbranch_scc1 .LBB0_684
	s_mov_b64 s[38:39], s[58:59]
	s_andn2_b64 vcc, exec, s[38:39]
	s_mov_b32 s0, s24
	s_cbranch_vccnz .LBB0_688
